# v58 + gate/up SwiGLU epilogue: packed f32 v_pk_mul/v_pk_fma split into scalar pairs (128 sites)
# baseline (speedup 1.0000x reference)
; __device__ __forceinline__ unsigned pk_bf16(float lo, float hi) { f32x2 v = {lo, hi}; bf16x2_t b = __builtin_convertvector(v, bf16x2_t); return __builtin_bit_cast(unsigned, b); }
;     __device__ __forceinline__ void operator()(const f32x4 (&acc)[2][2][4][2], const Unit& u, int wr, int wc, int fr, int fq) const {
;     ...
; #pragma unroll
;         for (int ai = 0; ai < 2; ++ai)
; #pragma unroll
;             for (int m = 0; m < 4; ++m) {
;                 float o[8]; const float rv = rsqrtf(rowss[row0 + ai * HALF + m * 16] * (1.0f / 1024.0f) + 1e-6f);
; #pragma unroll
;                 for (int n = 0; n < 2; ++n)
; #pragma unroll
;                     for (int j = 0; j < 4; ++j) { const float g = acc[ai][0][m][n][j] * rv + bz[0][n][j], up = acc[ai][1][m][n][j] * rv + bz[1][n][j];
;                         o[4 * n + j] = g * __builtin_amdgcn_rcpf(1.0f + __expf(-g)) * up; }
;                 u32x4 w; w.x = pk_bf16(o[0], o[1]); w.y = pk_bf16(o[2], o[3]); w.z = pk_bf16(o[4], o[5]); w.w = pk_bf16(o[6], o[7]);
;                 *(u32x4*)(act + (size_t)(row0 + ai * HALF + m * 16) * 2816 + col0) = w;
;             }
.LBB0_907:
	s_ashr_i32 s4, s34, 6
	s_mul_hi_i32 s5, s4, 0x5800
	s_mulk_i32 s4, 0x5800
	v_lshl_add_u32 v156, s34, 8, v162
	s_add_u32 s34, s14, s4
	s_addc_u32 s37, s15, s5
	s_lshl_b32 s4, s31, 8
	s_ashr_i32 s5, s4, 31
	s_lshl_b64 s[4:5], s[4:5], 2
	s_add_u32 s4, s34, s4
	s_addc_u32 s5, s37, s5
	s_add_u32 s4, s4, s30
	v_ashrrev_i32_e32 v157, 31, v156
	s_addc_u32 s5, s5, 0
	v_lshl_add_u64 v[158:159], v[156:157], 2, s[42:43]
	v_lshl_or_b32 v160, s31, 7, v164
	v_ashrrev_i32_e32 v161, 31, v160
	s_movk_i32 s12, 0x1600
	s_mov_b64 s[54:55], -1
	s_waitcnt vmcnt(8)
	v_fmamk_f32 v157, v147, 0x3a800000, v227
	s_nop 0
	v_rsq_f32_e32 v157, v157
	s_nop 0
	v_mov_b32_e32 v168, v157
	v_fma_f32 v142, v142, v168, v246
	v_fma_f32 v143, v143, v168, v247
	v_fma_f32 v134, v134, v168, v238
	v_fma_f32 v135, v135, v168, v239
	v_mul_f32_e32 v157, 0xbfb8aa3b, v142
	v_exp_f32_e32 v157, v157
	v_fma_f32 v136, v136, v168, v240
	v_fma_f32 v137, v137, v168, v241
	v_fma_f32 v138, v138, v168, v242
	v_fma_f32 v139, v139, v168, v243
	v_fma_f32 v130, v130, v168, v174
	v_fma_f32 v131, v131, v168, v175
	v_add_f32_e32 v157, 1.0, v157
	v_rcp_f32_e32 v170, v157
	v_mul_f32_e32 v157, 0xbfb8aa3b, v143
	v_exp_f32_e32 v157, v157
	v_fma_f32 v132, v132, v168, v176
	v_fma_f32 v133, v133, v168, v177
	v_add_f32_e32 v157, 1.0, v157
	v_rcp_f32_e32 v171, v157
	s_nop 0
	v_mul_f32_e32 v142, v142, v170
	v_mul_f32_e32 v143, v143, v171
	s_nop 0
	v_mul_f32_e32 v134, v134, v142
	v_mul_f32_e32 v135, v135, v143
	v_fma_f32 v142, v144, v168, v248
	v_fma_f32 v143, v145, v168, v249
	s_nop 0
	v_mul_f32_e32 v144, 0xbfb8aa3b, v142
	v_mul_f32_e32 v145, 0xbfb8aa3b, v143
	v_exp_f32_e32 v144, v144
	v_exp_f32_e32 v145, v145
	v_add_f32_e32 v144, 1.0, v144
	v_add_f32_e32 v145, 1.0, v145
	v_rcp_f32_e32 v144, v144
	v_rcp_f32_e32 v145, v145
	s_nop 0
	v_mul_f32_e32 v142, v142, v144
	v_mul_f32_e32 v143, v143, v145
	s_nop 0
	v_mul_f32_e32 v136, v136, v142
	v_mul_f32_e32 v137, v137, v143
	v_mul_f32_e32 v142, 0xbfb8aa3b, v138
	v_mul_f32_e32 v143, 0xbfb8aa3b, v139
	v_exp_f32_e32 v142, v142
	v_exp_f32_e32 v143, v143
	v_add_f32_e32 v142, 1.0, v142
	v_add_f32_e32 v143, 1.0, v143
	v_rcp_f32_e32 v142, v142
	v_rcp_f32_e32 v143, v143
	s_nop 0
	v_mul_f32_e32 v138, v138, v142
	v_mul_f32_e32 v139, v139, v143
	s_nop 0
	v_mul_f32_e32 v138, v130, v138
	v_mul_f32_e32 v139, v131, v139
	v_fma_f32 v130, v140, v168, v244
	v_fma_f32 v131, v141, v168, v245
	s_nop 0
	v_mul_f32_e32 v140, 0xbfb8aa3b, v130
	v_mul_f32_e32 v141, 0xbfb8aa3b, v131
	v_exp_f32_e32 v140, v140
	v_exp_f32_e32 v141, v141
	v_add_f32_e32 v140, 1.0, v140
	v_add_f32_e32 v141, 1.0, v141
	v_rcp_f32_e32 v140, v140
	v_rcp_f32_e32 v141, v141
	s_nop 0
	v_mul_f32_e32 v130, v130, v140
	v_mul_f32_e32 v131, v131, v141
	s_nop 0
	v_mul_f32_e32 v140, v132, v130
	v_mul_f32_e32 v141, v133, v131
	v_cvt_pk_bf16_f32 v130, v134, v135
	v_mov_b64_e32 v[134:135], s[2:3]
	v_cvt_pk_bf16_f32 v131, v136, v137
	v_cvt_pk_bf16_f32 v132, v138, v139
	v_mad_i64_i32 v[138:139], s[4:5], v156, s12, v[134:135]
	v_lshlrev_b64 v[136:137], 1, v[160:161]
	v_cvt_pk_bf16_f32 v133, v140, v141
	s_mov_b32 s99, 0
	v_lshl_add_u64 v[194:195], v[138:139], 0, v[136:137]
	global_store_dwordx4 v[194:195], v[130:133], off
	s_nop 1
	v_fmamk_f32 v131, v149, 0x3a800000, v227
	s_nop 0
	v_rsq_f32_e32 v131, v131
	s_nop 0
	v_mov_b32_e32 v132, v131
	v_fma_f32 v124, v124, v132, v246
	v_fma_f32 v125, v125, v132, v247
	v_fma_f32 v116, v116, v132, v238
	v_fma_f32 v117, v117, v132, v239
	v_mul_f32_e32 v131, 0xbfb8aa3b, v124
	v_exp_f32_e32 v131, v131
	v_fma_f32 v118, v118, v132, v240
	v_fma_f32 v119, v119, v132, v241
	v_fma_f32 v120, v120, v132, v242
	v_fma_f32 v121, v121, v132, v243
	v_fma_f32 v112, v112, v132, v174
	v_fma_f32 v113, v113, v132, v175
	v_add_f32_e32 v131, 1.0, v131
	v_rcp_f32_e32 v138, v131
	v_mul_f32_e32 v131, 0xbfb8aa3b, v125
	v_exp_f32_e32 v131, v131
	v_fma_f32 v114, v114, v132, v176
	v_fma_f32 v115, v115, v132, v177
	v_add_f32_e32 v131, 1.0, v131
	v_rcp_f32_e32 v139, v131
	s_nop 0
	v_mul_f32_e32 v124, v124, v138
	v_mul_f32_e32 v125, v125, v139
	s_nop 0
	v_mul_f32_e32 v116, v116, v124
	v_mul_f32_e32 v117, v117, v125
	v_fma_f32 v124, v126, v132, v248
	v_fma_f32 v125, v127, v132, v249
	s_nop 0
	v_mul_f32_e32 v126, 0xbfb8aa3b, v124
	v_mul_f32_e32 v127, 0xbfb8aa3b, v125
	v_exp_f32_e32 v126, v126
	v_exp_f32_e32 v127, v127
	v_add_f32_e32 v126, 1.0, v126
	v_add_f32_e32 v127, 1.0, v127
	v_rcp_f32_e32 v126, v126
	v_rcp_f32_e32 v127, v127
	s_nop 0
	v_mul_f32_e32 v124, v124, v126
	v_mul_f32_e32 v125, v125, v127
	s_nop 0
	v_mul_f32_e32 v118, v118, v124
	v_mul_f32_e32 v119, v119, v125
	v_mul_f32_e32 v124, 0xbfb8aa3b, v120
	v_mul_f32_e32 v125, 0xbfb8aa3b, v121
	v_exp_f32_e32 v124, v124
	v_exp_f32_e32 v125, v125
	v_add_f32_e32 v124, 1.0, v124
	v_add_f32_e32 v125, 1.0, v125
	v_rcp_f32_e32 v124, v124
	v_rcp_f32_e32 v125, v125
	s_nop 0
	v_mul_f32_e32 v120, v120, v124
	v_mul_f32_e32 v121, v121, v125
	s_nop 0
	v_mul_f32_e32 v120, v112, v120
	v_mul_f32_e32 v121, v113, v121
	v_fma_f32 v112, v122, v132, v244
	v_fma_f32 v113, v123, v132, v245
	s_nop 0
	v_mul_f32_e32 v122, 0xbfb8aa3b, v112
	v_mul_f32_e32 v123, 0xbfb8aa3b, v113
	v_exp_f32_e32 v122, v122
	v_exp_f32_e32 v123, v123
	v_add_f32_e32 v122, 1.0, v122
	v_add_f32_e32 v123, 1.0, v123
	v_rcp_f32_e32 v122, v122
	v_rcp_f32_e32 v123, v123
	s_nop 0
	v_mul_f32_e32 v112, v112, v122
	v_mul_f32_e32 v113, v113, v123
	s_nop 0
	v_mul_f32_e32 v122, v114, v112
	v_mul_f32_e32 v123, v115, v113
	v_cvt_pk_bf16_f32 v112, v116, v117
	s_mov_b32 s98, 0x16000
	v_cvt_pk_bf16_f32 v113, v118, v119
	v_cvt_pk_bf16_f32 v114, v120, v121
	v_cvt_pk_bf16_f32 v115, v122, v123
	v_lshl_add_u64 v[116:117], v[194:195], 0, s[98:99]
; __device__ __forceinline__ unsigned pk_bf16(float lo, float hi) { f32x2 v = {lo, hi}; bf16x2_t b = __builtin_convertvector(v, bf16x2_t); return __builtin_bit_cast(unsigned, b); }
;     __device__ __forceinline__ void operator()(const f32x4 (&acc)[2][2][4][2], const Unit& u, int wr, int wc, int fr, int fq) const {
;     ...
; #pragma unroll
;         for (int ai = 0; ai < 2; ++ai)
; #pragma unroll
;             for (int m = 0; m < 4; ++m) {
;                 float o[8]; const float rv = rsqrtf(rowss[row0 + ai * HALF + m * 16] * (1.0f / 1024.0f) + 1e-6f);
; #pragma unroll
;                 for (int n = 0; n < 2; ++n)
; #pragma unroll
;                     for (int j = 0; j < 4; ++j) { const float g = acc[ai][0][m][n][j] * rv + bz[0][n][j], up = acc[ai][1][m][n][j] * rv + bz[1][n][j];
;                         o[4 * n + j] = g * __builtin_amdgcn_rcpf(1.0f + __expf(-g)) * up; }
;                 u32x4 w; w.x = pk_bf16(o[0], o[1]); w.y = pk_bf16(o[2], o[3]); w.z = pk_bf16(o[4], o[5]); w.w = pk_bf16(o[6], o[7]);
;                 *(u32x4*)(act + (size_t)(row0 + ai * HALF + m * 16) * 2816 + col0) = w;
;             }
	global_store_dwordx4 v[116:117], v[112:115], off
	s_nop 1
	v_fmamk_f32 v113, v151, 0x3a800000, v227
	s_nop 0
	v_rsq_f32_e32 v113, v113
	s_nop 0
	v_mov_b32_e32 v114, v113
	v_fma_f32 v108, v108, v114, v246
	v_fma_f32 v109, v109, v114, v247
	v_fma_f32 v100, v100, v114, v238
	v_fma_f32 v101, v101, v114, v239
	v_mul_f32_e32 v113, 0xbfb8aa3b, v108
	v_exp_f32_e32 v113, v113
	v_fma_f32 v102, v102, v114, v240
	v_fma_f32 v103, v103, v114, v241
	v_fma_f32 v104, v104, v114, v242
	v_fma_f32 v105, v105, v114, v243
	v_fma_f32 v96, v96, v114, v174
	v_fma_f32 v97, v97, v114, v175
	v_add_f32_e32 v113, 1.0, v113
	v_rcp_f32_e32 v116, v113
	v_mul_f32_e32 v113, 0xbfb8aa3b, v109
	v_exp_f32_e32 v113, v113
	v_fma_f32 v98, v98, v114, v176
	v_fma_f32 v99, v99, v114, v177
	v_add_f32_e32 v113, 1.0, v113
	v_rcp_f32_e32 v117, v113
	s_nop 0
	v_mul_f32_e32 v108, v108, v116
	v_mul_f32_e32 v109, v109, v117
	s_nop 0
	v_mul_f32_e32 v100, v100, v108
	v_mul_f32_e32 v101, v101, v109
	v_fma_f32 v108, v110, v114, v248
	v_fma_f32 v109, v111, v114, v249
	s_nop 0
	v_mul_f32_e32 v110, 0xbfb8aa3b, v108
	v_mul_f32_e32 v111, 0xbfb8aa3b, v109
	v_exp_f32_e32 v110, v110
	v_exp_f32_e32 v111, v111
	v_add_f32_e32 v110, 1.0, v110
	v_add_f32_e32 v111, 1.0, v111
	v_rcp_f32_e32 v110, v110
	v_rcp_f32_e32 v111, v111
	s_nop 0
	v_mul_f32_e32 v108, v108, v110
	v_mul_f32_e32 v109, v109, v111
	s_nop 0
	v_mul_f32_e32 v102, v102, v108
	v_mul_f32_e32 v103, v103, v109
	v_mul_f32_e32 v108, 0xbfb8aa3b, v104
	v_mul_f32_e32 v109, 0xbfb8aa3b, v105
	v_exp_f32_e32 v108, v108
	v_exp_f32_e32 v109, v109
	v_add_f32_e32 v108, 1.0, v108
	v_add_f32_e32 v109, 1.0, v109
	v_rcp_f32_e32 v108, v108
	v_rcp_f32_e32 v109, v109
	s_nop 0
	v_mul_f32_e32 v104, v104, v108
	v_mul_f32_e32 v105, v105, v109
	s_nop 0
	v_mul_f32_e32 v104, v96, v104
	v_mul_f32_e32 v105, v97, v105
	v_fma_f32 v96, v106, v114, v244
	v_fma_f32 v97, v107, v114, v245
	s_nop 0
	v_mul_f32_e32 v106, 0xbfb8aa3b, v96
	v_mul_f32_e32 v107, 0xbfb8aa3b, v97
	v_exp_f32_e32 v106, v106
	v_exp_f32_e32 v107, v107
	v_add_f32_e32 v106, 1.0, v106
	v_add_f32_e32 v107, 1.0, v107
	v_rcp_f32_e32 v106, v106
	v_rcp_f32_e32 v107, v107
	s_nop 0
	v_mul_f32_e32 v96, v96, v106
	v_mul_f32_e32 v97, v97, v107
	s_nop 0
	v_mul_f32_e32 v106, v98, v96
	v_mul_f32_e32 v107, v99, v97
	v_cvt_pk_bf16_f32 v96, v100, v101
	s_mov_b32 s98, 0x2c000
	v_cvt_pk_bf16_f32 v97, v102, v103
	v_cvt_pk_bf16_f32 v98, v104, v105
	v_cvt_pk_bf16_f32 v99, v106, v107
	v_lshl_add_u64 v[100:101], v[194:195], 0, s[98:99]
	global_store_dwordx4 v[100:101], v[96:99], off
	s_nop 1
	v_fmamk_f32 v97, v153, 0x3a800000, v227
	s_nop 0
	v_rsq_f32_e32 v97, v97
	s_nop 0
	v_mov_b32_e32 v98, v97
	v_fma_f32 v92, v92, v98, v246
	v_fma_f32 v93, v93, v98, v247
	v_fma_f32 v84, v84, v98, v238
	v_fma_f32 v85, v85, v98, v239
	v_mul_f32_e32 v97, 0xbfb8aa3b, v92
	v_exp_f32_e32 v97, v97
	v_fma_f32 v86, v86, v98, v240
	v_fma_f32 v87, v87, v98, v241
	v_fma_f32 v88, v88, v98, v242
	v_fma_f32 v89, v89, v98, v243
	v_fma_f32 v80, v80, v98, v174
	v_fma_f32 v81, v81, v98, v175
	v_add_f32_e32 v97, 1.0, v97
	v_rcp_f32_e32 v100, v97
	v_mul_f32_e32 v97, 0xbfb8aa3b, v93
	v_exp_f32_e32 v97, v97
	v_fma_f32 v82, v82, v98, v176
	v_fma_f32 v83, v83, v98, v177
	v_add_f32_e32 v97, 1.0, v97
	v_rcp_f32_e32 v101, v97
	s_nop 0
	v_mul_f32_e32 v92, v92, v100
	v_mul_f32_e32 v93, v93, v101
	s_nop 0
	v_mul_f32_e32 v84, v84, v92
	v_mul_f32_e32 v85, v85, v93
	v_fma_f32 v92, v94, v98, v248
	v_fma_f32 v93, v95, v98, v249
	s_nop 0
	v_mul_f32_e32 v94, 0xbfb8aa3b, v92
	v_mul_f32_e32 v95, 0xbfb8aa3b, v93
	v_exp_f32_e32 v94, v94
	v_exp_f32_e32 v95, v95
	v_add_f32_e32 v94, 1.0, v94
	v_add_f32_e32 v95, 1.0, v95
	v_rcp_f32_e32 v94, v94
	v_rcp_f32_e32 v95, v95
	s_nop 0
	v_mul_f32_e32 v92, v92, v94
	v_mul_f32_e32 v93, v93, v95
	s_nop 0
	v_mul_f32_e32 v86, v86, v92
	v_mul_f32_e32 v87, v87, v93
	v_mul_f32_e32 v92, 0xbfb8aa3b, v88
	v_mul_f32_e32 v93, 0xbfb8aa3b, v89
	v_exp_f32_e32 v92, v92
	v_exp_f32_e32 v93, v93
	v_add_f32_e32 v92, 1.0, v92
	v_add_f32_e32 v93, 1.0, v93
	v_rcp_f32_e32 v92, v92
	v_rcp_f32_e32 v93, v93
	s_nop 0
	v_mul_f32_e32 v88, v88, v92
	v_mul_f32_e32 v89, v89, v93
	s_nop 0
	v_mul_f32_e32 v88, v80, v88
	v_mul_f32_e32 v89, v81, v89
	v_fma_f32 v80, v90, v98, v244
	v_fma_f32 v81, v91, v98, v245
	s_nop 0
	v_mul_f32_e32 v90, 0xbfb8aa3b, v80
	v_mul_f32_e32 v91, 0xbfb8aa3b, v81
	v_exp_f32_e32 v90, v90
	v_exp_f32_e32 v91, v91
	v_add_f32_e32 v90, 1.0, v90
	v_add_f32_e32 v91, 1.0, v91
	v_rcp_f32_e32 v90, v90
	v_rcp_f32_e32 v91, v91
	s_nop 0
	v_mul_f32_e32 v80, v80, v90
	v_mul_f32_e32 v81, v81, v91
	s_nop 0
	v_mul_f32_e32 v90, v82, v80
	v_mul_f32_e32 v91, v83, v81
	v_cvt_pk_bf16_f32 v80, v84, v85
	s_mov_b32 s98, 0x42000
	v_cvt_pk_bf16_f32 v81, v86, v87
	v_cvt_pk_bf16_f32 v82, v88, v89
	v_cvt_pk_bf16_f32 v83, v90, v91
	v_lshl_add_u64 v[84:85], v[194:195], 0, s[98:99]
	global_store_dwordx4 v[84:85], v[80:83], off
	s_nop 0
	s_nop 0
	v_fmamk_f32 v80, v155, 0x3a800000, v227
	s_nop 0
	v_rsq_f32_e32 v80, v80
	s_nop 0
	v_fma_f32 v76, v76, v80, v246
	v_fma_f32 v77, v77, v80, v247
	v_fma_f32 v68, v68, v80, v238
	v_fma_f32 v69, v69, v80, v239
	v_mul_f32_e32 v82, 0xbfb8aa3b, v76
	v_mul_f32_e32 v83, 0xbfb8aa3b, v77
	v_exp_f32_e32 v82, v82
	v_exp_f32_e32 v83, v83
	v_fma_f32 v70, v70, v80, v240
	v_fma_f32 v71, v71, v80, v241
	v_fma_f32 v72, v72, v80, v242
	v_fma_f32 v73, v73, v80, v243
	v_add_f32_e32 v82, 1.0, v82
	v_add_f32_e32 v83, 1.0, v83
	v_rcp_f32_e32 v82, v82
	v_rcp_f32_e32 v83, v83
	v_fma_f32 v64, v64, v80, v174
	v_fma_f32 v65, v65, v80, v175
	v_fma_f32 v66, v66, v80, v176
	v_fma_f32 v67, v67, v80, v177
	v_mul_f32_e32 v76, v76, v82
	v_mul_f32_e32 v77, v77, v83
	s_nop 0
	v_mul_f32_e32 v68, v68, v76
; __device__ __forceinline__ unsigned pk_bf16(float lo, float hi) { f32x2 v = {lo, hi}; bf16x2_t b = __builtin_convertvector(v, bf16x2_t); return __builtin_bit_cast(unsigned, b); }
;     __device__ __forceinline__ void operator()(const f32x4 (&acc)[2][2][4][2], const Unit& u, int wr, int wc, int fr, int fq) const {
;     ...
; #pragma unroll
;         for (int ai = 0; ai < 2; ++ai)
; #pragma unroll
;             for (int m = 0; m < 4; ++m) {
;                 float o[8]; const float rv = rsqrtf(rowss[row0 + ai * HALF + m * 16] * (1.0f / 1024.0f) + 1e-6f);
; #pragma unroll
;                 for (int n = 0; n < 2; ++n)
; #pragma unroll
;                     for (int j = 0; j < 4; ++j) { const float g = acc[ai][0][m][n][j] * rv + bz[0][n][j], up = acc[ai][1][m][n][j] * rv + bz[1][n][j];
;                         o[4 * n + j] = g * __builtin_amdgcn_rcpf(1.0f + __expf(-g)) * up; }
;                 u32x4 w; w.x = pk_bf16(o[0], o[1]); w.y = pk_bf16(o[2], o[3]); w.z = pk_bf16(o[4], o[5]); w.w = pk_bf16(o[6], o[7]);
;                 *(u32x4*)(act + (size_t)(row0 + ai * HALF + m * 16) * 2816 + col0) = w;
;             }
	v_mul_f32_e32 v69, v69, v77
	v_fma_f32 v76, v78, v80, v248
	v_fma_f32 v77, v79, v80, v249
	s_nop 0
	v_mul_f32_e32 v78, 0xbfb8aa3b, v76
	v_mul_f32_e32 v79, 0xbfb8aa3b, v77
	v_exp_f32_e32 v78, v78
	v_exp_f32_e32 v79, v79
	v_add_f32_e32 v78, 1.0, v78
	v_add_f32_e32 v79, 1.0, v79
	v_rcp_f32_e32 v78, v78
	v_rcp_f32_e32 v79, v79
	s_nop 0
	v_mul_f32_e32 v76, v76, v78
	v_mul_f32_e32 v77, v77, v79
	s_nop 0
	v_mul_f32_e32 v70, v70, v76
	v_mul_f32_e32 v71, v71, v77
	v_mul_f32_e32 v76, 0xbfb8aa3b, v72
	v_mul_f32_e32 v77, 0xbfb8aa3b, v73
	v_exp_f32_e32 v76, v76
	v_exp_f32_e32 v77, v77
	v_add_f32_e32 v76, 1.0, v76
	v_add_f32_e32 v77, 1.0, v77
	v_rcp_f32_e32 v76, v76
	v_rcp_f32_e32 v77, v77
	s_nop 0
	v_mul_f32_e32 v72, v72, v76
	v_mul_f32_e32 v73, v73, v77
	s_nop 0
	v_mul_f32_e32 v72, v64, v72
	v_mul_f32_e32 v73, v65, v73
	v_fma_f32 v64, v74, v80, v244
	v_fma_f32 v65, v75, v80, v245
	s_nop 0
	v_mul_f32_e32 v74, 0xbfb8aa3b, v64
	v_mul_f32_e32 v75, 0xbfb8aa3b, v65
	v_exp_f32_e32 v74, v74
	v_exp_f32_e32 v75, v75
	v_add_f32_e32 v74, 1.0, v74
	v_add_f32_e32 v75, 1.0, v75
	v_rcp_f32_e32 v74, v74
	v_rcp_f32_e32 v75, v75
	s_nop 0
	v_mul_f32_e32 v64, v64, v74
	v_mul_f32_e32 v65, v65, v75
	s_nop 0
	v_mul_f32_e32 v74, v66, v64
	v_mul_f32_e32 v75, v67, v65
	v_cvt_pk_bf16_f32 v64, v68, v69
	s_mov_b32 s98, 0xb0000
	v_cvt_pk_bf16_f32 v65, v70, v71
	v_cvt_pk_bf16_f32 v66, v72, v73
	v_cvt_pk_bf16_f32 v67, v74, v75
	v_lshl_add_u64 v[68:69], v[194:195], 0, s[98:99]
	global_store_dwordx4 v[68:69], v[64:67], off
	s_nop 0
	s_nop 0
	v_fmamk_f32 v64, v167, 0x3a800000, v227
	s_nop 0
	v_rsq_f32_e32 v64, v64
	s_nop 0
	v_fma_f32 v60, v60, v64, v246
	v_fma_f32 v61, v61, v64, v247
	v_fma_f32 v52, v52, v64, v238
	v_fma_f32 v53, v53, v64, v239
	v_mul_f32_e32 v66, 0xbfb8aa3b, v60
	v_mul_f32_e32 v67, 0xbfb8aa3b, v61
	v_exp_f32_e32 v66, v66
	v_exp_f32_e32 v67, v67
	v_fma_f32 v54, v54, v64, v240
	v_fma_f32 v55, v55, v64, v241
	v_fma_f32 v56, v56, v64, v242
	v_fma_f32 v57, v57, v64, v243
	v_add_f32_e32 v66, 1.0, v66
	v_add_f32_e32 v67, 1.0, v67
	v_rcp_f32_e32 v66, v66
	v_rcp_f32_e32 v67, v67
	v_fma_f32 v48, v48, v64, v174
	v_fma_f32 v49, v49, v64, v175
	v_fma_f32 v50, v50, v64, v176
	v_fma_f32 v51, v51, v64, v177
	v_mul_f32_e32 v60, v60, v66
	v_mul_f32_e32 v61, v61, v67
	s_nop 0
	v_mul_f32_e32 v52, v52, v60
	v_mul_f32_e32 v53, v53, v61
	v_fma_f32 v60, v62, v64, v248
	v_fma_f32 v61, v63, v64, v249
	s_nop 0
	v_mul_f32_e32 v62, 0xbfb8aa3b, v60
	v_mul_f32_e32 v63, 0xbfb8aa3b, v61
	v_exp_f32_e32 v62, v62
	v_exp_f32_e32 v63, v63
	v_add_f32_e32 v62, 1.0, v62
	v_add_f32_e32 v63, 1.0, v63
	v_rcp_f32_e32 v62, v62
	v_rcp_f32_e32 v63, v63
	s_nop 0
	v_mul_f32_e32 v60, v60, v62
	v_mul_f32_e32 v61, v61, v63
	s_nop 0
	v_mul_f32_e32 v54, v54, v60
	v_mul_f32_e32 v55, v55, v61
	v_mul_f32_e32 v60, 0xbfb8aa3b, v56
	v_mul_f32_e32 v61, 0xbfb8aa3b, v57
	v_exp_f32_e32 v60, v60
	v_exp_f32_e32 v61, v61
	v_add_f32_e32 v60, 1.0, v60
	v_add_f32_e32 v61, 1.0, v61
	v_rcp_f32_e32 v60, v60
	v_rcp_f32_e32 v61, v61
	s_nop 0
	v_mul_f32_e32 v56, v56, v60
	v_mul_f32_e32 v57, v57, v61
	s_nop 0
	v_mul_f32_e32 v56, v48, v56
	v_mul_f32_e32 v57, v49, v57
	v_fma_f32 v48, v58, v64, v244
	v_fma_f32 v49, v59, v64, v245
	s_nop 0
	v_mul_f32_e32 v58, 0xbfb8aa3b, v48
	v_mul_f32_e32 v59, 0xbfb8aa3b, v49
	v_exp_f32_e32 v58, v58
	v_exp_f32_e32 v59, v59
	v_add_f32_e32 v58, 1.0, v58
	v_add_f32_e32 v59, 1.0, v59
	v_rcp_f32_e32 v58, v58
	v_rcp_f32_e32 v59, v59
	s_nop 0
	v_mul_f32_e32 v48, v48, v58
	v_mul_f32_e32 v49, v49, v59
	s_nop 0
	v_mul_f32_e32 v58, v50, v48
	v_mul_f32_e32 v59, v51, v49
	v_cvt_pk_bf16_f32 v48, v52, v53
	s_mov_b32 s98, 0xc6000
	v_cvt_pk_bf16_f32 v49, v54, v55
	v_cvt_pk_bf16_f32 v50, v56, v57
	v_cvt_pk_bf16_f32 v51, v58, v59
	v_lshl_add_u64 v[52:53], v[194:195], 0, s[98:99]
	global_store_dwordx4 v[52:53], v[48:51], off
	s_nop 0
	s_nop 0
	v_fmamk_f32 v48, v173, 0x3a800000, v227
	s_nop 0
	v_rsq_f32_e32 v48, v48
	s_nop 0
	v_fma_f32 v28, v28, v48, v246
	v_fma_f32 v29, v29, v48, v247
	v_fma_f32 v20, v20, v48, v238
	v_fma_f32 v21, v21, v48, v239
	v_mul_f32_e32 v50, 0xbfb8aa3b, v28
	v_mul_f32_e32 v51, 0xbfb8aa3b, v29
	v_exp_f32_e32 v50, v50
	v_exp_f32_e32 v51, v51
	v_fma_f32 v22, v22, v48, v240
	v_fma_f32 v23, v23, v48, v241
	v_fma_f32 v24, v24, v48, v242
; __device__ __forceinline__ unsigned pk_bf16(float lo, float hi) { f32x2 v = {lo, hi}; bf16x2_t b = __builtin_convertvector(v, bf16x2_t); return __builtin_bit_cast(unsigned, b); }
; #define PG8_BAR __builtin_amdgcn_s_barrier()
;     __device__ __forceinline__ void operator()(const f32x4 (&acc)[2][2][4][2], const Unit& u, int wr, int wc, int fr, int fq) const {
;     ...
; #pragma unroll
;         for (int ai = 0; ai < 2; ++ai)
; #pragma unroll
;             for (int m = 0; m < 4; ++m) {
;                 float o[8]; const float rv = rsqrtf(rowss[row0 + ai * HALF + m * 16] * (1.0f / 1024.0f) + 1e-6f);
; #pragma unroll
;                 for (int n = 0; n < 2; ++n)
; #pragma unroll
;                     for (int j = 0; j < 4; ++j) { const float g = acc[ai][0][m][n][j] * rv + bz[0][n][j], up = acc[ai][1][m][n][j] * rv + bz[1][n][j];
;                         o[4 * n + j] = g * __builtin_amdgcn_rcpf(1.0f + __expf(-g)) * up; }
;                 u32x4 w; w.x = pk_bf16(o[0], o[1]); w.y = pk_bf16(o[2], o[3]); w.z = pk_bf16(o[4], o[5]); w.w = pk_bf16(o[6], o[7]);
;                 *(u32x4*)(act + (size_t)(row0 + ai * HALF + m * 16) * 2816 + col0) = w;
;             }
; template <class Epi, class Sched, bool ALIGN_EPI = false, bool SP2 = false, bool F16 = false>
; __device__ __forceinline__ void gemm_phase(PG8_LAS unsigned char* lds, const Gemm g, const Sched& S, const Epi& E) {
;     ...
;         if (!has_next) break;
; #pragma unroll
;         for (int a = 0; a < 2; ++a)
; #pragma unroll
;             for (int b = 0; b < 2; ++b)
; #pragma unroll
;                 for (int m = 0; m < 4; ++m)
; #pragma unroll
;                     for (int n = 0; n < 2; ++n) acc[a][b][m][n] = (f32x4){0.f, 0.f, 0.f, 0.f};
;         cur = nxt; cA = nA; cB = nB; ++ui;
;         if constexpr (ALIGN_EPI) { if (wr == 1) PG8_BAR; }
	v_fma_f32 v25, v25, v48, v243
	v_add_f32_e32 v50, 1.0, v50
	v_add_f32_e32 v51, 1.0, v51
	v_rcp_f32_e32 v50, v50
	v_rcp_f32_e32 v51, v51
	v_fma_f32 v16, v16, v48, v174
	v_fma_f32 v17, v17, v48, v175
	v_fma_f32 v18, v18, v48, v176
	v_fma_f32 v19, v19, v48, v177
	v_mul_f32_e32 v28, v28, v50
	v_mul_f32_e32 v29, v29, v51
	s_nop 0
	v_mul_f32_e32 v20, v20, v28
	v_mul_f32_e32 v21, v21, v29
	v_fma_f32 v28, v30, v48, v248
	v_fma_f32 v29, v31, v48, v249
	s_nop 0
	v_mul_f32_e32 v30, 0xbfb8aa3b, v28
	v_mul_f32_e32 v31, 0xbfb8aa3b, v29
	v_exp_f32_e32 v30, v30
	v_exp_f32_e32 v31, v31
	v_add_f32_e32 v30, 1.0, v30
	v_add_f32_e32 v31, 1.0, v31
	v_rcp_f32_e32 v30, v30
	v_rcp_f32_e32 v31, v31
	s_nop 0
	v_mul_f32_e32 v28, v28, v30
	v_mul_f32_e32 v29, v29, v31
	s_nop 0
	v_mul_f32_e32 v22, v22, v28
	v_mul_f32_e32 v23, v23, v29
	v_mul_f32_e32 v28, 0xbfb8aa3b, v24
	v_mul_f32_e32 v29, 0xbfb8aa3b, v25
	v_exp_f32_e32 v28, v28
	v_exp_f32_e32 v29, v29
	v_add_f32_e32 v28, 1.0, v28
	v_add_f32_e32 v29, 1.0, v29
	v_rcp_f32_e32 v28, v28
	v_rcp_f32_e32 v29, v29
	s_nop 0
	v_mul_f32_e32 v24, v24, v28
	v_mul_f32_e32 v25, v25, v29
	s_nop 0
	v_mul_f32_e32 v24, v16, v24
	v_mul_f32_e32 v25, v17, v25
	v_fma_f32 v16, v26, v48, v244
	v_fma_f32 v17, v27, v48, v245
	s_nop 0
	v_mul_f32_e32 v26, 0xbfb8aa3b, v16
	v_mul_f32_e32 v27, 0xbfb8aa3b, v17
	v_exp_f32_e32 v26, v26
	v_exp_f32_e32 v27, v27
	v_add_f32_e32 v26, 1.0, v26
	v_add_f32_e32 v27, 1.0, v27
	v_rcp_f32_e32 v26, v26
	v_rcp_f32_e32 v27, v27
	s_nop 0
	v_mul_f32_e32 v16, v16, v26
	v_mul_f32_e32 v17, v17, v27
	s_nop 0
	v_mul_f32_e32 v26, v18, v16
	v_mul_f32_e32 v27, v19, v17
	v_cvt_pk_bf16_f32 v16, v20, v21
	s_mov_b32 s98, 0xdc000
	v_cvt_pk_bf16_f32 v17, v22, v23
	v_cvt_pk_bf16_f32 v18, v24, v25
	v_cvt_pk_bf16_f32 v19, v26, v27
	v_lshl_add_u64 v[20:21], v[194:195], 0, s[98:99]
	global_store_dwordx4 v[20:21], v[16:19], off
	s_nop 0
	s_nop 0
	v_fmamk_f32 v16, v250, 0x3a800000, v227
	s_nop 0
	v_rsq_f32_e32 v16, v16
	s_nop 0
	v_fma_f32 v12, v12, v16, v246
	v_fma_f32 v13, v13, v16, v247
	v_fma_f32 v4, v4, v16, v238
	v_fma_f32 v5, v5, v16, v239
	v_mul_f32_e32 v18, 0xbfb8aa3b, v12
	v_mul_f32_e32 v19, 0xbfb8aa3b, v13
	v_exp_f32_e32 v18, v18
	v_exp_f32_e32 v19, v19
	v_fma_f32 v6, v6, v16, v240
	v_fma_f32 v7, v7, v16, v241
	v_fma_f32 v8, v8, v16, v242
	v_fma_f32 v9, v9, v16, v243
	v_add_f32_e32 v18, 1.0, v18
	v_add_f32_e32 v19, 1.0, v19
	v_rcp_f32_e32 v18, v18
	v_rcp_f32_e32 v19, v19
	v_fma_f32 v0, v0, v16, v174
	v_fma_f32 v1, v1, v16, v175
	v_fma_f32 v2, v2, v16, v176
	v_fma_f32 v3, v3, v16, v177
	s_andn2_b64 vcc, exec, s[40:41]
	v_mul_f32_e32 v12, v12, v18
	v_mul_f32_e32 v13, v13, v19
	s_nop 0
	v_mul_f32_e32 v4, v4, v12
	v_mul_f32_e32 v5, v5, v13
	v_fma_f32 v12, v14, v16, v248
	v_fma_f32 v13, v15, v16, v249
	s_nop 0
	v_mul_f32_e32 v14, 0xbfb8aa3b, v12
	v_mul_f32_e32 v15, 0xbfb8aa3b, v13
	v_exp_f32_e32 v14, v14
	v_exp_f32_e32 v15, v15
	v_add_f32_e32 v14, 1.0, v14
	v_add_f32_e32 v15, 1.0, v15
	v_rcp_f32_e32 v14, v14
	v_rcp_f32_e32 v15, v15
	s_nop 0
	v_mul_f32_e32 v12, v12, v14
	v_mul_f32_e32 v13, v13, v15
	s_nop 0
	v_mul_f32_e32 v6, v6, v12
	v_mul_f32_e32 v7, v7, v13
	v_mul_f32_e32 v12, 0xbfb8aa3b, v8
	v_mul_f32_e32 v13, 0xbfb8aa3b, v9
	v_exp_f32_e32 v12, v12
	v_exp_f32_e32 v13, v13
	v_add_f32_e32 v12, 1.0, v12
	v_add_f32_e32 v13, 1.0, v13
	v_rcp_f32_e32 v12, v12
	v_rcp_f32_e32 v13, v13
	s_nop 0
	v_mul_f32_e32 v8, v8, v12
	v_mul_f32_e32 v9, v9, v13
	s_nop 0
	v_mul_f32_e32 v8, v0, v8
	v_mul_f32_e32 v9, v1, v9
	v_fma_f32 v0, v10, v16, v244
	v_fma_f32 v1, v11, v16, v245
	s_nop 0
	v_mul_f32_e32 v10, 0xbfb8aa3b, v0
	v_mul_f32_e32 v11, 0xbfb8aa3b, v1
	v_exp_f32_e32 v10, v10
	v_exp_f32_e32 v11, v11
	v_add_f32_e32 v10, 1.0, v10
	v_add_f32_e32 v11, 1.0, v11
	v_rcp_f32_e32 v10, v10
	v_rcp_f32_e32 v11, v11
	s_nop 0
	v_mul_f32_e32 v0, v0, v10
	v_mul_f32_e32 v1, v1, v11
	s_nop 0
	v_mul_f32_e32 v10, v2, v0
	v_mul_f32_e32 v11, v3, v1
	v_cvt_pk_bf16_f32 v0, v4, v5
	s_mov_b32 s98, 0xf2000
	v_cvt_pk_bf16_f32 v1, v6, v7
	v_cvt_pk_bf16_f32 v2, v8, v9
	v_cvt_pk_bf16_f32 v3, v10, v11
	v_lshl_add_u64 v[4:5], v[194:195], 0, s[98:99]
	global_store_dwordx4 v[4:5], v[0:3], off
	s_cbranch_vccnz .LBB0_900
	s_andn2_b64 vcc, exec, s[0:1]
	s_cbranch_vccnz .LBB0_899
	s_barrier
	s_branch .LBB0_899
